# H stores of the first phase and of the layer-0 post phase written through (sc1) so the following grid barrier has less to write back
# speedup vs baseline: 1.0137x; 1.0024x over previous
.LBB0_19:
	v_add_u32_e32 v42, -3, v36
	v_add_u32_e32 v40, -2, v36
	v_ashrrev_i32_e32 v43, 31, v42
	v_ashrrev_i32_e32 v41, 31, v40
	v_lshlrev_b64 v[44:45], 12, v[42:43]
	v_lshlrev_b64 v[46:47], 12, v[40:41]
	v_lshl_add_u64 v[56:57], v[34:35], 0, v[44:45]
	v_lshl_add_u64 v[68:69], v[34:35], 0, v[46:47]
	global_load_dwordx4 v[44:47], v[56:57], off nt
	global_load_dwordx4 v[48:51], v[56:57], off offset:1024 nt
	global_load_dwordx4 v[52:55], v[56:57], off offset:2048 nt
	s_nop 0
	global_load_dwordx4 v[56:59], v[56:57], off offset:3072 nt
	s_nop 0
	global_load_dwordx4 v[60:63], v[68:69], off nt
	v_lshlrev_b64 v[42:43], 11, v[42:43]
	v_lshl_add_u64 v[42:43], v[38:39], 0, v[42:43]
	v_lshlrev_b64 v[40:41], 11, v[40:41]
	v_lshl_add_u64 v[40:41], v[38:39], 0, v[40:41]
	v_add_u32_e32 v32, s3, v32
	s_waitcnt vmcnt(4)
	v_mul_f32_e32 v37, v45, v45
	v_mul_f32_e32 v64, v47, v47
	s_waitcnt vmcnt(3)
	v_mul_f32_e32 v65, v49, v49
	v_mul_f32_e32 v66, v51, v51
	s_waitcnt vmcnt(2)
	v_mul_f32_e32 v67, v53, v53
	v_mul_f32_e32 v70, v55, v55
	v_fmac_f32_e32 v37, v44, v44
	v_fmac_f32_e32 v64, v46, v46
	v_fmac_f32_e32 v65, v48, v48
	v_fmac_f32_e32 v66, v50, v50
	s_waitcnt vmcnt(1)
	v_mul_f32_e32 v71, v57, v57
	v_mul_f32_e32 v72, v59, v59
	v_fmac_f32_e32 v67, v52, v52
	v_fmac_f32_e32 v70, v54, v54
	v_add_f32_e32 v37, v37, v64
	v_add_f32_e32 v64, v65, v66
	v_fmac_f32_e32 v71, v56, v56
	v_fmac_f32_e32 v72, v58, v58
	v_add_f32_e32 v65, v67, v70
	v_add_f32_e32 v37, v37, v64
	v_add_f32_e32 v66, v71, v72
	v_add_f32_e32 v37, v37, v65
	v_add_f32_e32 v37, v37, v66
	s_nop 1
	v_add_f32_dpp v37, v37, v37 quad_perm:[1,0,3,2] row_mask:0xf bank_mask:0xf bound_ctrl:1
	s_nop 1
	v_add_f32_dpp v37, v37, v37 quad_perm:[2,3,0,1] row_mask:0xf bank_mask:0xf bound_ctrl:1
	s_nop 1
	v_add_f32_dpp v37, v37, v37 row_half_mirror row_mask:0xf bank_mask:0xf bound_ctrl:1
	s_nop 1
	v_add_f32_dpp v37, v37, v37 row_mirror row_mask:0xf bank_mask:0xf bound_ctrl:1
	s_nop 0
	v_readlane_b32 s1, v37, 16
	v_readlane_b32 s6, v37, 48
	v_readlane_b32 s0, v37, 0
	v_readlane_b32 s2, v37, 32
	v_mov_b32_e32 v37, s1
	v_mov_b32_e32 v64, s6
	v_add_f32_e32 v37, s0, v37
	v_add_f32_e32 v64, s2, v64
	v_add_f32_e32 v37, v37, v64
	v_fmamk_f32 v37, v37, 0x3a800000, v188
	v_mul_f32_e32 v64, 0x4f800000, v37
	v_cmp_gt_f32_e32 vcc, s49, v37
	s_nop 1
	v_cndmask_b32_e32 v37, v37, v64, vcc
	v_sqrt_f32_e32 v64, v37
	s_nop 0
	v_add_u32_e32 v65, -1, v64
	v_add_u32_e32 v66, 1, v64
	v_fma_f32 v67, -v65, v64, v37
	v_fma_f32 v70, -v66, v64, v37
	v_cmp_ge_f32_e64 s[0:1], 0, v67
	s_nop 1
	v_cndmask_b32_e64 v64, v64, v65, s[0:1]
	v_cmp_lt_f32_e64 s[0:1], 0, v70
	s_nop 1
	v_cndmask_b32_e64 v64, v64, v66, s[0:1]
	v_mul_f32_e32 v65, 0x37800000, v64
	v_cndmask_b32_e32 v64, v64, v65, vcc
	v_cmp_class_f32_e32 vcc, v37, v189
	s_nop 1
	v_cndmask_b32_e32 v37, v64, v37, vcc
	v_div_scale_f32 v70, s[0:1], v37, v37, 1.0
	v_rcp_f32_e32 v72, v70
	v_div_scale_f32 v71, vcc, 1.0, v37, 1.0
	v_fma_f32 v64, -v70, v72, 1.0
	v_fmac_f32_e32 v72, v64, v72
	v_mul_f32_e32 v73, v71, v72
	v_fma_f32 v64, -v70, v73, v71
	v_fmac_f32_e32 v73, v64, v72
	global_load_dwordx4 v[64:67], v[68:69], off offset:1024 nt
	v_fma_f32 v70, -v70, v73, v71
	v_div_fmas_f32 v70, v70, v72, v73
	v_div_fixup_f32 v37, v70, v37, 1.0
	v_mul_f32_e32 v85, v45, v37
	v_mul_f32_e32 v87, v44, v37
	v_mul_f32_e32 v88, v47, v37
	v_mul_f32_e32 v89, v46, v37
	v_mul_f32_e32 v79, v49, v37
	v_mul_f32_e32 v82, v48, v37
	v_mul_f32_e32 v84, v51, v37
	v_mul_f32_e32 v86, v50, v37
	v_mul_f32_e32 v78, v52, v37
	s_waitcnt vmcnt(1)
	v_mul_f32_e32 v71, v61, v61
	v_mul_f32_e32 v76, v53, v37
	v_mul_f32_e32 v81, v55, v37
	v_mul_f32_e32 v83, v54, v37
	v_mul_f32_e32 v74, v57, v37
	v_mul_f32_e32 v75, v56, v37
	v_mul_f32_e32 v77, v59, v37
	v_mul_f32_e32 v80, v58, v37
	v_mul_f32_e32 v37, v63, v63
	v_fmac_f32_e32 v71, v60, v60
	v_fmac_f32_e32 v37, v62, v62
	v_add_f32_e32 v37, v71, v37
	v_fma_f32 v89, v18, v89, v12
	v_fma_f32 v85, v21, v85, v11
	v_fma_f32 v79, v25, v79, v3
	v_fma_f32 v87, v0, v87, v10
	v_fma_f32 v82, v22, v82, v2
	v_fma_f32 v78, v26, v78, v6
	v_fma_f32 v76, v29, v76, v7
	v_fma_f32 v75, v30, v75, v14
	v_fma_f32 v74, v33, v74, v15
	v_fma_f32 v81, v27, v81, v9
	v_fma_f32 v77, v31, v77, v17
	s_waitcnt vmcnt(0)
	v_mul_f32_e32 v44, v65, v65
	v_mul_f32_e32 v45, v67, v67
	v_fmac_f32_e32 v44, v64, v64
	v_fmac_f32_e32 v45, v66, v66
	v_add_f32_e32 v52, v44, v45
	global_load_dwordx4 v[44:47], v[68:69], off offset:2048 nt
	global_load_dwordx4 v[48:51], v[68:69], off offset:3072 nt
	v_add_f32_e32 v37, v37, v52
	s_waitcnt vmcnt(1)
	v_mul_f32_e32 v53, v45, v45
	v_mul_f32_e32 v54, v47, v47
	v_fmac_f32_e32 v53, v44, v44
	v_fmac_f32_e32 v54, v46, v46
	v_add_f32_e32 v53, v53, v54
	s_waitcnt vmcnt(0)
	v_mul_f32_e32 v54, v49, v49
	v_mul_f32_e32 v55, v51, v51
	v_fmac_f32_e32 v54, v48, v48
	v_fmac_f32_e32 v55, v50, v50
	v_add_f32_e32 v54, v54, v55
	v_add_f32_e32 v37, v37, v53
	v_add_f32_e32 v37, v37, v54
	s_nop 1
	v_add_f32_dpp v37, v37, v37 quad_perm:[1,0,3,2] row_mask:0xf bank_mask:0xf bound_ctrl:1
	s_nop 1
	v_add_f32_dpp v37, v37, v37 quad_perm:[2,3,0,1] row_mask:0xf bank_mask:0xf bound_ctrl:1
	s_nop 1
	v_add_f32_dpp v37, v37, v37 row_half_mirror row_mask:0xf bank_mask:0xf bound_ctrl:1
	s_nop 1
	v_add_f32_dpp v37, v37, v37 row_mirror row_mask:0xf bank_mask:0xf bound_ctrl:1
	s_nop 0
	v_readlane_b32 s1, v37, 16
	v_readlane_b32 s6, v37, 48
	v_readlane_b32 s0, v37, 0
	v_readlane_b32 s2, v37, 32
	v_mov_b32_e32 v37, s1
	v_mov_b32_e32 v52, s6
	v_add_f32_e32 v37, s0, v37
	v_add_f32_e32 v52, s2, v52
	v_add_f32_e32 v37, v37, v52
	v_fmamk_f32 v37, v37, 0x3a800000, v188
	v_mul_f32_e32 v52, 0x4f800000, v37
	v_cmp_gt_f32_e32 vcc, s49, v37
	s_nop 1
	v_cndmask_b32_e32 v37, v37, v52, vcc
	v_sqrt_f32_e32 v52, v37
	s_nop 0
	v_add_u32_e32 v53, -1, v52
	v_fma_f32 v54, -v53, v52, v37
	v_cmp_ge_f32_e64 s[0:1], 0, v54
	v_add_u32_e32 v54, 1, v52
	s_nop 0
	v_cndmask_b32_e64 v53, v52, v53, s[0:1]
	v_fma_f32 v52, -v54, v52, v37
	v_cmp_lt_f32_e64 s[0:1], 0, v52
	s_nop 1
	v_cndmask_b32_e64 v52, v53, v54, s[0:1]
	v_mul_f32_e32 v53, 0x37800000, v52
	v_cndmask_b32_e32 v52, v52, v53, vcc
	v_cmp_class_f32_e32 vcc, v37, v189
	s_nop 1
	v_cndmask_b32_e32 v37, v52, v37, vcc
	v_div_scale_f32 v52, s[0:1], v37, v37, 1.0
	v_rcp_f32_e32 v53, v52
	s_nop 0
	v_fma_f32 v54, -v52, v53, 1.0
	v_fmac_f32_e32 v53, v54, v53
	v_div_scale_f32 v54, vcc, 1.0, v37, 1.0
	v_mul_f32_e32 v55, v54, v53
	v_fma_f32 v56, -v52, v55, v54
	v_fmac_f32_e32 v55, v56, v53
	v_fma_f32 v52, -v52, v55, v54
	v_div_fmas_f32 v52, v52, v53, v55
	v_div_fixup_f32 v37, v52, v37, 1.0
	v_mul_f32_e32 v94, v44, v37
	v_add_u32_e32 v44, -1, v36
	v_mul_f32_e32 v92, v45, v37
	v_ashrrev_i32_e32 v45, 31, v44
	v_mul_f32_e32 v97, v47, v37
	v_mul_f32_e32 v99, v46, v37
	v_lshlrev_b64 v[46:47], 12, v[44:45]
	v_mul_f32_e32 v93, v51, v37
	v_mul_f32_e32 v96, v50, v37
	v_lshl_add_u64 v[50:51], v[34:35], 0, v[46:47]
	v_mul_f32_e32 v90, v49, v37
	v_mul_f32_e32 v91, v48, v37
	global_load_dwordx4 v[46:49], v[50:51], off nt
	global_load_dwordx4 v[52:55], v[50:51], off offset:1024 nt
	v_mul_f32_e32 v101, v61, v37
	v_mul_f32_e32 v103, v60, v37
	v_mul_f32_e32 v104, v63, v37
	v_mul_f32_e32 v105, v62, v37
	v_mul_f32_e32 v95, v65, v37
	v_mul_f32_e32 v98, v64, v37
	v_mul_f32_e32 v100, v67, v37
	v_mul_f32_e32 v102, v66, v37
	v_lshlrev_b64 v[44:45], 11, v[44:45]
	v_lshl_add_u64 v[44:45], v[38:39], 0, v[44:45]
	s_waitcnt vmcnt(1)
	v_mul_f32_e32 v37, v47, v47
	v_mul_f32_e32 v56, v49, v49
	v_fmac_f32_e32 v37, v46, v46
	v_fmac_f32_e32 v56, v48, v48
	v_add_f32_e32 v37, v37, v56
	s_waitcnt vmcnt(0)
	v_mul_f32_e32 v56, v53, v53
	v_mul_f32_e32 v57, v55, v55
	v_fmac_f32_e32 v56, v52, v52
	v_fmac_f32_e32 v57, v54, v54
	v_add_f32_e32 v64, v56, v57
	global_load_dwordx4 v[56:59], v[50:51], off offset:2048 nt
	global_load_dwordx4 v[60:63], v[50:51], off offset:3072 nt
	v_add_f32_e32 v37, v37, v64
	s_waitcnt vmcnt(1)
	v_mul_f32_e32 v50, v57, v57
	v_mul_f32_e32 v51, v59, v59
	v_fmac_f32_e32 v50, v56, v56
	v_fmac_f32_e32 v51, v58, v58
	v_add_f32_e32 v50, v50, v51
	s_waitcnt vmcnt(0)
	v_mul_f32_e32 v51, v61, v61
	v_mul_f32_e32 v65, v63, v63
	v_fmac_f32_e32 v51, v60, v60
	v_fmac_f32_e32 v65, v62, v62
	v_add_f32_e32 v51, v51, v65
	v_add_f32_e32 v37, v37, v50
	v_add_f32_e32 v37, v37, v51
	s_nop 1
	v_add_f32_dpp v37, v37, v37 quad_perm:[1,0,3,2] row_mask:0xf bank_mask:0xf bound_ctrl:1
	s_nop 1
	v_add_f32_dpp v37, v37, v37 quad_perm:[2,3,0,1] row_mask:0xf bank_mask:0xf bound_ctrl:1
	s_nop 1
	v_add_f32_dpp v37, v37, v37 row_half_mirror row_mask:0xf bank_mask:0xf bound_ctrl:1
	s_nop 1
	v_add_f32_dpp v37, v37, v37 row_mirror row_mask:0xf bank_mask:0xf bound_ctrl:1
	s_nop 0
	v_readlane_b32 s1, v37, 16
	v_readlane_b32 s6, v37, 48
	v_readlane_b32 s0, v37, 0
	v_readlane_b32 s2, v37, 32
	v_mov_b32_e32 v37, s1
	v_mov_b32_e32 v50, s6
	v_add_f32_e32 v37, s0, v37
	v_add_f32_e32 v50, s2, v50
	v_add_f32_e32 v37, v37, v50
	v_fmamk_f32 v37, v37, 0x3a800000, v188
	v_mul_f32_e32 v50, 0x4f800000, v37
	v_cmp_gt_f32_e32 vcc, s49, v37
	s_nop 1
	v_cndmask_b32_e32 v37, v37, v50, vcc
	v_sqrt_f32_e32 v50, v37
	s_nop 0
	v_add_u32_e32 v51, -1, v50
	v_fma_f32 v64, -v51, v50, v37
	v_cmp_ge_f32_e64 s[0:1], 0, v64
	v_add_u32_e32 v64, 1, v50
	s_nop 0
	v_cndmask_b32_e64 v51, v50, v51, s[0:1]
	v_fma_f32 v50, -v64, v50, v37
	v_cmp_lt_f32_e64 s[0:1], 0, v50
	s_nop 1
	v_cndmask_b32_e64 v50, v51, v64, s[0:1]
	v_mul_f32_e32 v51, 0x37800000, v50
	v_cndmask_b32_e32 v50, v50, v51, vcc
	v_cmp_class_f32_e32 vcc, v37, v189
	s_nop 1
	v_cndmask_b32_e32 v37, v50, v37, vcc
	v_div_scale_f32 v50, s[0:1], v37, v37, 1.0
	v_rcp_f32_e32 v51, v50
	s_nop 0
	v_fma_f32 v64, -v50, v51, 1.0
	v_fmac_f32_e32 v51, v64, v51
	v_div_scale_f32 v64, vcc, 1.0, v37, 1.0
	v_mul_f32_e32 v65, v64, v51
	v_fma_f32 v66, -v50, v65, v64
	v_fmac_f32_e32 v65, v66, v51
	v_fma_f32 v50, -v50, v65, v64
	v_div_fmas_f32 v50, v50, v51, v65
	v_div_fixup_f32 v37, v50, v37, 1.0
	v_mul_f32_e32 v106, v47, v37
	v_mul_f32_e32 v107, v46, v37
	v_mul_f32_e32 v108, v49, v37
	v_mul_f32_e32 v109, v48, v37
	v_mul_f32_e32 v46, v53, v37
	v_mul_f32_e32 v49, v52, v37
	v_mul_f32_e32 v52, v55, v37
	v_mul_f32_e32 v55, v54, v37
	v_mul_f32_e32 v47, v57, v37
	v_mul_f32_e32 v50, v56, v37
	v_mul_f32_e32 v53, v59, v37
	v_mul_f32_e32 v56, v58, v37
	v_mul_f32_e32 v48, v61, v37
	v_mul_f32_e32 v51, v60, v37
	v_mul_f32_e32 v54, v63, v37
	v_mul_f32_e32 v57, v62, v37
	v_ashrrev_i32_e32 v37, 31, v36
	v_lshlrev_b64 v[58:59], 12, v[36:37]
	v_lshl_add_u64 v[58:59], v[34:35], 0, v[58:59]
	global_load_dwordx4 v[62:65], v[58:59], off nt
	global_load_dwordx4 v[110:113], v[58:59], off offset:1024 nt
	global_load_dwordx4 v[114:117], v[58:59], off offset:2048 nt
	global_load_dwordx4 v[118:121], v[58:59], off offset:3072 nt
	v_fma_f32 v52, v23, v52, v5
	v_fma_f32 v49, v22, v49, v2
	v_fma_f32 v46, v25, v46, v3
	v_fma_f32 v53, v27, v53, v9
	v_fma_f32 v50, v26, v50, v6
	v_fma_f32 v47, v29, v47, v7
	v_fma_f32 v54, v31, v54, v17
	v_fma_f32 v51, v30, v51, v14
	v_fma_f32 v48, v33, v48, v15
	s_waitcnt vmcnt(3)
	v_mul_f32_e32 v60, v63, v63
	v_mul_f32_e32 v61, v65, v65
	v_fmac_f32_e32 v60, v62, v62
	v_fmac_f32_e32 v61, v64, v64
	v_add_f32_e32 v60, v60, v61
	s_waitcnt vmcnt(2)
	v_mul_f32_e32 v61, v111, v111
	v_mul_f32_e32 v66, v113, v113
	s_waitcnt vmcnt(1)
	v_mul_f32_e32 v58, v115, v115
	v_mul_f32_e32 v59, v117, v117
	v_fmac_f32_e32 v61, v110, v110
	v_fmac_f32_e32 v66, v112, v112
	v_fmac_f32_e32 v58, v114, v114
	v_fmac_f32_e32 v59, v116, v116
	v_add_f32_e32 v61, v61, v66
	v_add_f32_e32 v58, v58, v59
	s_waitcnt vmcnt(0)
	v_mul_f32_e32 v59, v119, v119
	v_mul_f32_e32 v66, v121, v121
	v_fmac_f32_e32 v59, v118, v118
	v_fmac_f32_e32 v66, v120, v120
	v_add_f32_e32 v60, v60, v61
	v_add_f32_e32 v59, v59, v66
	v_add_f32_e32 v58, v60, v58
	v_add_f32_e32 v58, v58, v59
	s_nop 1
	v_add_f32_dpp v58, v58, v58 quad_perm:[1,0,3,2] row_mask:0xf bank_mask:0xf bound_ctrl:1
	s_nop 1
	v_add_f32_dpp v58, v58, v58 quad_perm:[2,3,0,1] row_mask:0xf bank_mask:0xf bound_ctrl:1
	s_nop 1
	v_add_f32_dpp v58, v58, v58 row_half_mirror row_mask:0xf bank_mask:0xf bound_ctrl:1
	s_nop 1
	v_add_f32_dpp v58, v58, v58 row_mirror row_mask:0xf bank_mask:0xf bound_ctrl:1
	s_nop 0
	v_readlane_b32 s1, v58, 16
	v_readlane_b32 s6, v58, 48
	v_readlane_b32 s0, v58, 0
	v_readlane_b32 s2, v58, 32
	v_mov_b32_e32 v58, s1
	v_mov_b32_e32 v59, s6
	v_add_f32_e32 v58, s0, v58
	v_add_f32_e32 v59, s2, v59
	v_add_f32_e32 v58, v58, v59
	v_fmamk_f32 v58, v58, 0x3a800000, v188
	v_mul_f32_e32 v59, 0x4f800000, v58
	v_cmp_gt_f32_e32 vcc, s49, v58
	s_nop 1
	v_cndmask_b32_e32 v58, v58, v59, vcc
	v_sqrt_f32_e32 v59, v58
	s_nop 0
	v_add_u32_e32 v60, -1, v59
	v_fma_f32 v61, -v60, v59, v58
	v_cmp_ge_f32_e64 s[0:1], 0, v61
	v_add_u32_e32 v61, 1, v59
	s_nop 0
	v_cndmask_b32_e64 v60, v59, v60, s[0:1]
	v_fma_f32 v59, -v61, v59, v58
	v_cmp_lt_f32_e64 s[0:1], 0, v59
	s_nop 1
	v_cndmask_b32_e64 v59, v60, v61, s[0:1]
	v_mul_f32_e32 v60, 0x37800000, v59
	v_cndmask_b32_e32 v59, v59, v60, vcc
	v_cmp_class_f32_e32 vcc, v58, v189
	s_nop 1
	v_cndmask_b32_e32 v58, v59, v58, vcc
	v_div_scale_f32 v59, s[0:1], v58, v58, 1.0
	v_rcp_f32_e32 v60, v59
	s_nop 0
	v_fma_f32 v61, -v59, v60, 1.0
	v_fmac_f32_e32 v60, v61, v60
	v_div_scale_f32 v61, vcc, 1.0, v58, 1.0
	v_mul_f32_e32 v66, v61, v60
	v_fma_f32 v67, -v59, v66, v61
	v_fmac_f32_e32 v66, v67, v60
	v_fma_f32 v59, -v59, v66, v61
	v_div_fmas_f32 v59, v59, v60, v66
	v_div_fixup_f32 v73, v59, v58, 1.0
	v_mul_f32_e32 v58, v63, v73
	v_mul_f32_e32 v63, v110, v73
	v_fma_f32 v110, v19, v88, v13
	v_cvt_pk_bf16_f32 v88, v87, v85
	v_cvt_pk_bf16_f32 v89, v89, v110
	global_store_dwordx2 v[42:43], v[88:89], off sc1
	v_fma_f32 v85, v20, v86, v4
	v_fma_f32 v86, v23, v84, v5
	v_cvt_pk_bf16_f32 v84, v82, v79
	v_fma_f32 v79, v24, v83, v8
	v_cvt_pk_bf16_f32 v85, v85, v86
	global_store_dwordx2 v[42:43], v[84:85], off offset:512 sc1
	v_cvt_pk_bf16_f32 v78, v78, v76
	v_cvt_pk_bf16_f32 v79, v79, v81
	global_store_dwordx2 v[42:43], v[78:79], off offset:1024 sc1
	v_fma_f32 v76, v28, v80, v16
	v_cvt_pk_bf16_f32 v74, v75, v74
	v_cvt_pk_bf16_f32 v75, v76, v77
	global_store_dwordx2 v[42:43], v[74:75], off offset:1536 sc1
	v_fma_f32 v43, v18, v105, v12
	v_fma_f32 v42, v0, v103, v10
	v_fma_f32 v74, v19, v104, v13
	v_fma_f32 v75, v21, v101, v11
	v_cvt_pk_bf16_f32 v42, v42, v75
	v_cvt_pk_bf16_f32 v43, v43, v74
	global_store_dwordx2 v[40:41], v[42:43], off sc1
	v_fma_f32 v43, v20, v102, v4
	v_fma_f32 v42, v22, v98, v2
	v_fma_f32 v74, v23, v100, v5
	v_fma_f32 v75, v25, v95, v3
	v_cvt_pk_bf16_f32 v42, v42, v75
	v_cvt_pk_bf16_f32 v43, v43, v74
	global_store_dwordx2 v[40:41], v[42:43], off offset:512 sc1
	v_fma_f32 v43, v24, v99, v8
	v_fma_f32 v42, v26, v94, v6
	v_fma_f32 v74, v27, v97, v9
	v_fma_f32 v75, v29, v92, v7
	v_cvt_pk_bf16_f32 v42, v42, v75
	v_cvt_pk_bf16_f32 v43, v43, v74
	global_store_dwordx2 v[40:41], v[42:43], off offset:1024 sc1
	v_fma_f32 v43, v28, v96, v16
	v_fma_f32 v42, v30, v91, v14
	v_fma_f32 v74, v31, v93, v17
	v_fma_f32 v75, v33, v90, v15
	v_cvt_pk_bf16_f32 v42, v42, v75
	v_cvt_pk_bf16_f32 v43, v43, v74
	global_store_dwordx2 v[40:41], v[42:43], off offset:1536 sc1
	v_fma_f32 v41, v18, v109, v12
	v_fma_f32 v40, v0, v107, v10
	v_fma_f32 v42, v19, v108, v13
	v_fma_f32 v43, v21, v106, v11
	v_cvt_pk_bf16_f32 v40, v40, v43
	v_cvt_pk_bf16_f32 v41, v41, v42
	v_lshlrev_b64 v[42:43], 11, v[36:37]
	v_fma_f32 v37, v20, v55, v4
	global_store_dwordx2 v[44:45], v[40:41], off sc1
	v_cvt_pk_bf16_f32 v40, v49, v46
	v_cvt_pk_bf16_f32 v41, v37, v52
	v_fma_f32 v55, v24, v56, v8
	global_store_dwordx2 v[44:45], v[40:41], off offset:512 sc1
	v_cvt_pk_bf16_f32 v40, v50, v47
	v_cvt_pk_bf16_f32 v41, v55, v53
	v_mul_f32_e32 v62, v62, v73
	v_mul_f32_e32 v66, v65, v73
	v_mul_f32_e32 v70, v64, v73
	v_fma_f32 v56, v28, v57, v16
	global_store_dwordx2 v[44:45], v[40:41], off offset:1024 sc1
	v_cvt_pk_bf16_f32 v40, v51, v48
	v_cvt_pk_bf16_f32 v41, v56, v54
	v_mul_f32_e32 v59, v111, v73
	v_mul_f32_e32 v67, v113, v73
	v_mul_f32_e32 v71, v112, v73
	v_lshl_add_u64 v[42:43], v[38:39], 0, v[42:43]
	v_fma_f32 v57, v18, v70, v12
	v_fma_f32 v66, v19, v66, v13
	v_fma_f32 v62, v0, v62, v10
	v_fma_f32 v58, v21, v58, v11
	global_store_dwordx2 v[44:45], v[40:41], off offset:1536 sc1
	v_cvt_pk_bf16_f32 v40, v62, v58
	v_cvt_pk_bf16_f32 v41, v57, v66
	v_mul_f32_e32 v60, v115, v73
	v_mul_f32_e32 v64, v114, v73
	v_mul_f32_e32 v68, v117, v73
	v_mul_f32_e32 v72, v116, v73
	v_cmp_lt_i32_e32 vcc, s61, v32
	v_fma_f32 v70, v20, v71, v4
	v_fma_f32 v67, v23, v67, v5
	v_fma_f32 v63, v22, v63, v2
	v_fma_f32 v59, v25, v59, v3
	global_store_dwordx2 v[42:43], v[40:41], off sc1
	v_cvt_pk_bf16_f32 v40, v63, v59
	v_cvt_pk_bf16_f32 v41, v70, v67
	v_mul_f32_e32 v61, v119, v73
	v_mul_f32_e32 v65, v118, v73
	v_mul_f32_e32 v69, v121, v73
	v_mul_f32_e32 v73, v120, v73
	v_add_u32_e32 v36, s3, v36
	s_or_b64 s[38:39], vcc, s[38:39]
	v_fma_f32 v71, v24, v72, v8
	v_fma_f32 v68, v27, v68, v9
	v_fma_f32 v64, v26, v64, v6
	v_fma_f32 v60, v29, v60, v7
	global_store_dwordx2 v[42:43], v[40:41], off offset:512 sc1
	v_cvt_pk_bf16_f32 v40, v64, v60
	v_cvt_pk_bf16_f32 v41, v71, v68
	v_fma_f32 v72, v28, v73, v16
	v_fma_f32 v69, v31, v69, v17
	v_fma_f32 v65, v30, v65, v14
	v_fma_f32 v61, v33, v61, v15
	global_store_dwordx2 v[42:43], v[40:41], off offset:1024 sc1
	v_cvt_pk_bf16_f32 v40, v65, v61
	v_cvt_pk_bf16_f32 v41, v72, v69
	global_store_dwordx2 v[42:43], v[40:41], off offset:1536 sc1
	s_andn2_b64 exec, exec, s[38:39]
	s_cbranch_execnz .LBB0_19

.LBB0_33:
	v_add_u32_e32 v50, -3, v122
	v_ashrrev_i32_e32 v51, 31, v50
	v_lshlrev_b64 v[162:163], 12, v[50:51]
	v_lshl_add_u64 v[52:53], v[114:115], 0, v[162:163]
	v_lshlrev_b64 v[160:161], 11, v[50:51]
	v_lshl_add_u64 v[50:51], v[116:117], 0, v[160:161]
	global_load_dwordx4 v[110:113], v[52:53], off nt
	global_load_dwordx2 v[170:171], v[50:51], off
	global_load_dwordx4 v[106:109], v[52:53], off offset:1024 nt
	global_load_dwordx2 v[168:169], v[50:51], off offset:512
	global_load_dwordx4 v[102:105], v[52:53], off offset:2048 nt
	global_load_dwordx2 v[166:167], v[50:51], off offset:1024
	global_load_dwordx4 v[98:101], v[52:53], off offset:3072 nt
	global_load_dwordx2 v[164:165], v[50:51], off offset:1536
	v_ashrrev_i32_e32 v123, 31, v122
	v_lshlrev_b64 v[126:127], 12, v[122:123]
	v_lshlrev_b64 v[124:125], 11, v[122:123]
	v_add_u32_e32 v50, -2, v122
	v_ashrrev_i32_e32 v51, 31, v50
	v_lshlrev_b64 v[150:151], 12, v[50:51]
	v_lshl_add_u64 v[52:53], v[114:115], 0, v[150:151]
	v_lshlrev_b64 v[140:141], 11, v[50:51]
	v_lshl_add_u64 v[50:51], v[116:117], 0, v[140:141]
	global_load_dwordx4 v[94:97], v[52:53], off nt
	global_load_dwordx2 v[158:159], v[50:51], off
	global_load_dwordx4 v[90:93], v[52:53], off offset:1024 nt
	global_load_dwordx2 v[156:157], v[50:51], off offset:512
	global_load_dwordx4 v[86:89], v[52:53], off offset:2048 nt
	global_load_dwordx2 v[154:155], v[50:51], off offset:1024
	global_load_dwordx4 v[82:85], v[52:53], off offset:3072 nt
	global_load_dwordx2 v[152:153], v[50:51], off offset:1536
	v_add_u32_e32 v50, -1, v122
	v_ashrrev_i32_e32 v51, 31, v50
	v_lshlrev_b64 v[138:139], 12, v[50:51]
	v_lshlrev_b64 v[136:137], 11, v[50:51]
	v_lshl_add_u64 v[52:53], v[114:115], 0, v[138:139]
	v_lshl_add_u64 v[50:51], v[116:117], 0, v[136:137]
	global_load_dwordx4 v[78:81], v[52:53], off nt
	global_load_dwordx2 v[148:149], v[50:51], off
	global_load_dwordx4 v[74:77], v[52:53], off offset:1024 nt
	global_load_dwordx2 v[146:147], v[50:51], off offset:512
	global_load_dwordx4 v[70:73], v[52:53], off offset:2048 nt
	global_load_dwordx2 v[144:145], v[50:51], off offset:1024
	global_load_dwordx4 v[66:69], v[52:53], off offset:3072 nt
	global_load_dwordx2 v[142:143], v[50:51], off offset:1536
	v_lshl_add_u64 v[50:51], v[114:115], 0, v[126:127]
	v_lshl_add_u64 v[128:129], v[116:117], 0, v[124:125]
	v_lshl_add_u64 v[162:163], v[120:121], 0, v[162:163]
	global_load_dwordx4 v[62:65], v[50:51], off nt
	global_load_dwordx2 v[134:135], v[128:129], off
	global_load_dwordx4 v[58:61], v[50:51], off offset:1024 nt
	global_load_dwordx2 v[132:133], v[128:129], off offset:512
	global_load_dwordx4 v[54:57], v[50:51], off offset:2048 nt
	global_load_dwordx2 v[130:131], v[128:129], off offset:1024
	s_nop 0
	global_load_dwordx4 v[50:53], v[50:51], off offset:3072 nt
	s_nop 0
	global_load_dwordx2 v[128:129], v[128:129], off offset:1536
	v_lshl_add_u64 v[160:161], v[118:119], 0, v[160:161]
	v_add_u32_e32 v172, s3, v172
	v_add_u32_e32 v122, s3, v122
	s_waitcnt vmcnt(30)
	v_and_b32_e32 v177, 0xffff0000, v170
	v_and_b32_e32 v179, 0xffff0000, v171
	v_lshlrev_b32_e32 v176, 16, v170
	v_lshlrev_b32_e32 v178, 16, v171
	v_mul_f32_e32 v0, v177, v177
	v_mul_f32_e32 v123, v179, v179
	v_fmac_f32_e32 v0, v176, v176
	v_fmac_f32_e32 v123, v178, v178
	s_waitcnt vmcnt(28)
	v_and_b32_e32 v173, 0xffff0000, v168
	v_and_b32_e32 v175, 0xffff0000, v169
	v_add_f32_e32 v0, v0, v123
	v_lshlrev_b32_e32 v171, 16, v168
	v_lshlrev_b32_e32 v174, 16, v169
	v_mul_f32_e32 v123, v173, v173
	v_mul_f32_e32 v168, v175, v175
	v_fmac_f32_e32 v123, v171, v171
	v_fmac_f32_e32 v168, v174, v174
	v_add_f32_e32 v123, v123, v168
	s_waitcnt vmcnt(26)
	v_and_b32_e32 v169, 0xffff0000, v166
	v_lshlrev_b32_e32 v170, 16, v167
	v_and_b32_e32 v167, 0xffff0000, v167
	v_add_f32_e32 v0, v0, v123
	v_lshlrev_b32_e32 v168, 16, v166
	v_mul_f32_e32 v123, v169, v169
	v_mul_f32_e32 v166, v167, v167
	v_fmac_f32_e32 v123, v168, v168
	v_fmac_f32_e32 v166, v170, v170
	v_add_f32_e32 v123, v123, v166
	v_add_f32_e32 v166, v0, v123
	s_waitcnt vmcnt(24)
	v_lshlrev_b32_e32 v0, 16, v164
	v_and_b32_e32 v123, 0xffff0000, v164
	v_lshlrev_b32_e32 v164, 16, v165
	v_and_b32_e32 v165, 0xffff0000, v165
	v_mul_f32_e32 v180, v123, v123
	v_mul_f32_e32 v181, v165, v165
	v_fmac_f32_e32 v180, v0, v0
	v_fmac_f32_e32 v181, v164, v164
	v_add_f32_e32 v180, v180, v181
	v_add_f32_e32 v166, v166, v180
	s_nop 1
	v_add_f32_dpp v166, v166, v166 quad_perm:[1,0,3,2] row_mask:0xf bank_mask:0xf bound_ctrl:1
	s_nop 1
	v_add_f32_dpp v166, v166, v166 quad_perm:[2,3,0,1] row_mask:0xf bank_mask:0xf bound_ctrl:1
	s_nop 1
	v_add_f32_dpp v166, v166, v166 row_half_mirror row_mask:0xf bank_mask:0xf bound_ctrl:1
	s_nop 1
	v_add_f32_dpp v166, v166, v166 row_mirror row_mask:0xf bank_mask:0xf bound_ctrl:1
	s_nop 0
	v_readlane_b32 s1, v166, 16
	v_readlane_b32 s6, v166, 48
	v_readlane_b32 s0, v166, 0
	v_readlane_b32 s2, v166, 32
	v_mov_b32_e32 v166, s1
	v_mov_b32_e32 v180, s6
	v_add_f32_e32 v166, s0, v166
	v_add_f32_e32 v180, s2, v180
	v_add_f32_e32 v166, v166, v180
	v_fmamk_f32 v166, v166, 0x3a800000, v188
	v_cmp_gt_f32_e32 vcc, s49, v166
	v_mul_f32_e32 v180, 0x4f800000, v166
	s_nop 0
	v_cndmask_b32_e32 v166, v166, v180, vcc
	v_sqrt_f32_e32 v180, v166
	s_nop 0
	v_add_u32_e32 v181, -1, v180
	v_fma_f32 v182, -v181, v180, v166
	v_cmp_ge_f32_e64 s[0:1], 0, v182
	v_add_u32_e32 v182, 1, v180
	s_nop 0
	v_cndmask_b32_e64 v181, v180, v181, s[0:1]
	v_fma_f32 v180, -v182, v180, v166
	v_cmp_lt_f32_e64 s[0:1], 0, v180
	s_nop 1
	v_cndmask_b32_e64 v180, v181, v182, s[0:1]
	v_mul_f32_e32 v181, 0x37800000, v180
	v_cndmask_b32_e32 v180, v180, v181, vcc
	v_cmp_class_f32_e32 vcc, v166, v189
	s_nop 1
	v_cndmask_b32_e32 v166, v180, v166, vcc
	v_div_scale_f32 v180, s[0:1], v166, v166, 1.0
	v_rcp_f32_e32 v181, v180
	s_nop 0
	v_fma_f32 v182, -v180, v181, 1.0
	v_fmac_f32_e32 v181, v182, v181
	v_div_scale_f32 v182, vcc, 1.0, v166, 1.0
	v_mul_f32_e32 v183, v182, v181
	v_fma_f32 v184, -v180, v183, v182
	v_fmac_f32_e32 v183, v184, v181
	v_fma_f32 v180, -v180, v183, v182
	v_div_fmas_f32 v180, v180, v181, v183
	v_div_fixup_f32 v166, v180, v166, 1.0
	v_mul_f32_e32 v177, v177, v166
	v_mul_f32_e32 v179, v179, v166
	v_mul_f32_e32 v173, v173, v166
	v_mul_f32_e32 v175, v175, v166
	v_mul_f32_e32 v176, v176, v166
	v_mul_f32_e32 v178, v178, v166
	v_fma_f32 v113, v3, v179, v113
	v_fma_f32 v111, v5, v177, v111
	v_mul_f32_e32 v171, v171, v166
	v_mul_f32_e32 v174, v174, v166
	v_fma_f32 v109, v15, v175, v109
	v_fma_f32 v107, v17, v173, v107
	v_mul_f32_e32 v169, v169, v166
	v_mul_f32_e32 v167, v167, v166
	v_fma_f32 v112, v2, v178, v112
	v_fmac_f32_e32 v110, v4, v176
	v_mul_f32_e32 v176, v111, v111
	v_mul_f32_e32 v177, v113, v113
	v_fma_f32 v108, v14, v174, v108
	v_fmac_f32_e32 v106, v16, v171
	v_mul_f32_e32 v171, v107, v107
	v_mul_f32_e32 v173, v109, v109
	v_mul_f32_e32 v168, v168, v166
	v_mul_f32_e32 v170, v170, v166
	v_fma_f32 v105, v27, v167, v105
	v_fma_f32 v103, v29, v169, v103
	v_mul_f32_e32 v123, v123, v166
	v_mul_f32_e32 v165, v165, v166
	v_fmac_f32_e32 v176, v110, v110
	v_fmac_f32_e32 v177, v112, v112
	v_fmac_f32_e32 v171, v106, v106
	v_fmac_f32_e32 v173, v108, v108
	v_fma_f32 v104, v26, v170, v104
	v_fmac_f32_e32 v102, v28, v168
	v_mul_f32_e32 v167, v103, v103
	v_mul_f32_e32 v168, v105, v105
	v_mul_f32_e32 v0, v0, v166
	v_mul_f32_e32 v164, v164, v166
	v_fma_f32 v101, v39, v165, v101
	v_fma_f32 v99, v41, v123, v99
	v_add_f32_e32 v176, v176, v177
	v_add_f32_e32 v171, v171, v173
	v_fmac_f32_e32 v167, v102, v102
	v_fmac_f32_e32 v168, v104, v104
	v_fma_f32 v100, v38, v164, v100
	v_fmac_f32_e32 v98, v40, v0
	v_mul_f32_e32 v0, v99, v99
	v_mul_f32_e32 v123, v101, v101
	v_add_f32_e32 v171, v176, v171
	v_add_f32_e32 v167, v167, v168
	v_fmac_f32_e32 v0, v98, v98
	v_fmac_f32_e32 v123, v100, v100
	v_add_f32_e32 v167, v167, v171
	v_add_f32_e32 v0, v0, v123
	v_add_f32_e32 v0, v0, v167
	s_nop 1
	s_nop 1
	v_add_f32_dpp v0, v0, v0 quad_perm:[1,0,3,2] row_mask:0xf bank_mask:0xf bound_ctrl:1
	s_nop 1
	s_nop 1
	v_add_f32_dpp v0, v0, v0 quad_perm:[2,3,0,1] row_mask:0xf bank_mask:0xf bound_ctrl:1
	s_nop 1
	v_add_f32_dpp v0, v0, v0 row_half_mirror row_mask:0xf bank_mask:0xf bound_ctrl:1
	s_nop 1
	v_add_f32_dpp v0, v0, v0 row_mirror row_mask:0xf bank_mask:0xf bound_ctrl:1
	s_nop 0
	v_readlane_b32 s1, v0, 16
	v_readlane_b32 s6, v0, 48
	v_readlane_b32 s0, v0, 0
	v_readlane_b32 s2, v0, 32
	v_mov_b32_e32 v0, s1
	v_mov_b32_e32 v123, s6
	v_add_f32_e32 v0, s0, v0
	v_add_f32_e32 v123, s2, v123
	v_add_f32_e32 v0, v0, v123
	v_fmamk_f32 v0, v0, 0x3a800000, v188
	v_cmp_gt_f32_e32 vcc, s49, v0
	v_mul_f32_e32 v123, 0x4f800000, v0
	s_nop 0
	v_cndmask_b32_e32 v0, v0, v123, vcc
	v_sqrt_f32_e32 v123, v0
	s_nop 0
	v_add_u32_e32 v162, -1, v123
	v_fma_f32 v163, -v162, v123, v0
	v_cmp_ge_f32_e64 s[0:1], 0, v163
	v_add_u32_e32 v163, 1, v123
	s_nop 0
	v_cndmask_b32_e64 v162, v123, v162, s[0:1]
	v_fma_f32 v123, -v163, v123, v0
	v_cmp_lt_f32_e64 s[0:1], 0, v123
	s_nop 1
	v_cndmask_b32_e64 v123, v162, v163, s[0:1]
	v_mul_f32_e32 v162, 0x37800000, v123
	v_cndmask_b32_e32 v123, v123, v162, vcc
	v_cmp_class_f32_e32 vcc, v0, v189
	s_nop 1
	v_cndmask_b32_e32 v0, v123, v0, vcc
	v_div_scale_f32 v123, s[0:1], v0, v0, 1.0
	v_rcp_f32_e32 v162, v123
	s_nop 0
	v_fma_f32 v163, -v123, v162, 1.0
	v_fmac_f32_e32 v162, v163, v162
	v_div_scale_f32 v163, vcc, 1.0, v0, 1.0
	v_mul_f32_e32 v164, v163, v162
	v_fma_f32 v165, -v123, v164, v163
	v_fmac_f32_e32 v164, v165, v162
	v_fma_f32 v123, -v123, v164, v163
	v_div_fmas_f32 v123, v123, v162, v164
	v_div_fixup_f32 v0, v123, v0, 1.0
	v_mul_f32_e32 v111, v111, v0
	v_mul_f32_e32 v110, v110, v0
	v_mul_f32_e32 v107, v107, v0
	v_mul_f32_e32 v106, v106, v0
	v_mul_f32_e32 v103, v103, v0
	v_mul_f32_e32 v102, v102, v0
	v_mul_f32_e32 v98, v98, v0
	v_mul_f32_e32 v113, v113, v0
	v_mul_f32_e32 v112, v112, v0
	v_fma_f32 v110, v8, v110, v10
	v_fma_f32 v111, v9, v111, v11
	v_mul_f32_e32 v109, v109, v0
	v_mul_f32_e32 v108, v108, v0
	v_fma_f32 v106, v20, v106, v22
	v_fma_f32 v107, v21, v107, v23
	v_mul_f32_e32 v105, v105, v0
	v_mul_f32_e32 v104, v104, v0
	v_fma_f32 v102, v32, v102, v34
	v_fma_f32 v103, v33, v103, v35
	v_mul_f32_e32 v99, v99, v0
	v_mul_f32_e32 v101, v101, v0
	v_fma_f32 v98, v44, v98, v46
	v_fma_f32 v112, v6, v112, v12
	v_fma_f32 v113, v7, v113, v13
	v_cvt_pk_bf16_f32 v110, v110, v111
	v_cvt_pk_bf16_f32 v111, v112, v113
	global_store_dwordx2 v[160:161], v[110:111], off sc1
	v_fma_f32 v108, v18, v108, v24
	v_fma_f32 v109, v19, v109, v25
	v_cvt_pk_bf16_f32 v106, v106, v107
	v_cvt_pk_bf16_f32 v107, v108, v109
	global_store_dwordx2 v[160:161], v[106:107], off offset:512 sc1
	v_fma_f32 v104, v30, v104, v36
	v_fma_f32 v105, v31, v105, v37
	v_cvt_pk_bf16_f32 v102, v102, v103
	v_cvt_pk_bf16_f32 v103, v104, v105
	global_store_dwordx2 v[160:161], v[102:103], off offset:1024 sc1
	v_mul_f32_e32 v0, v100, v0
	v_fma_f32 v100, v43, v101, v49
	v_fma_f32 v99, v45, v99, v47
	v_cvt_pk_bf16_f32 v98, v98, v99
	v_fma_f32 v0, v42, v0, v48
	v_cvt_pk_bf16_f32 v99, v0, v100
	global_store_dwordx2 v[160:161], v[98:99], off offset:1536 sc1
	s_waitcnt vmcnt(26)
	v_and_b32_e32 v98, 0xffff0000, v158
	v_and_b32_e32 v100, 0xffff0000, v159
	v_lshlrev_b32_e32 v0, 16, v158
	v_lshlrev_b32_e32 v99, 16, v159
	v_mul_f32_e32 v101, v98, v98
	v_mul_f32_e32 v102, v100, v100
	v_fmac_f32_e32 v101, v0, v0
	v_fmac_f32_e32 v102, v99, v99
	s_waitcnt vmcnt(24)
	v_and_b32_e32 v103, 0xffff0000, v156
	v_and_b32_e32 v105, 0xffff0000, v157
	v_add_f32_e32 v101, v101, v102
	v_lshlrev_b32_e32 v102, 16, v156
	v_lshlrev_b32_e32 v104, 16, v157
	v_mul_f32_e32 v106, v103, v103
	v_mul_f32_e32 v107, v105, v105
	v_fmac_f32_e32 v106, v102, v102
	v_fmac_f32_e32 v107, v104, v104
	v_add_f32_e32 v106, v106, v107
	s_waitcnt vmcnt(22)
	v_and_b32_e32 v107, 0xffff0000, v154
	v_and_b32_e32 v109, 0xffff0000, v155
	v_add_f32_e32 v101, v101, v106
	v_lshlrev_b32_e32 v106, 16, v154
	v_lshlrev_b32_e32 v108, 16, v155
	v_mul_f32_e32 v110, v107, v107
	v_mul_f32_e32 v111, v109, v109
	v_fmac_f32_e32 v110, v106, v106
	v_fmac_f32_e32 v111, v108, v108
	v_add_f32_e32 v110, v110, v111
	s_waitcnt vmcnt(20)
	v_and_b32_e32 v111, 0xffff0000, v152
	v_and_b32_e32 v113, 0xffff0000, v153
	v_add_f32_e32 v101, v101, v110
	v_lshlrev_b32_e32 v110, 16, v152
	v_lshlrev_b32_e32 v112, 16, v153
	v_mul_f32_e32 v123, v111, v111
	v_mul_f32_e32 v152, v113, v113
	v_fmac_f32_e32 v123, v110, v110
	v_fmac_f32_e32 v152, v112, v112
	v_add_f32_e32 v123, v123, v152
	v_add_f32_e32 v101, v101, v123
	s_nop 1
	v_add_f32_dpp v101, v101, v101 quad_perm:[1,0,3,2] row_mask:0xf bank_mask:0xf bound_ctrl:1
	s_nop 1
	v_add_f32_dpp v101, v101, v101 quad_perm:[2,3,0,1] row_mask:0xf bank_mask:0xf bound_ctrl:1
	s_nop 1
	v_add_f32_dpp v101, v101, v101 row_half_mirror row_mask:0xf bank_mask:0xf bound_ctrl:1
	s_nop 1
	v_add_f32_dpp v101, v101, v101 row_mirror row_mask:0xf bank_mask:0xf bound_ctrl:1
	s_nop 0
	v_readlane_b32 s1, v101, 16
	v_readlane_b32 s6, v101, 48
	v_readlane_b32 s0, v101, 0
	v_readlane_b32 s2, v101, 32
	v_mov_b32_e32 v101, s1
	v_mov_b32_e32 v123, s6
	v_add_f32_e32 v101, s0, v101
	v_add_f32_e32 v123, s2, v123
	v_add_f32_e32 v101, v101, v123
	v_fmamk_f32 v101, v101, 0x3a800000, v188
	v_cmp_gt_f32_e32 vcc, s49, v101
	v_mul_f32_e32 v123, 0x4f800000, v101
	s_nop 0
	v_cndmask_b32_e32 v101, v101, v123, vcc
	v_sqrt_f32_e32 v123, v101
	s_nop 0
	v_add_u32_e32 v152, -1, v123
	v_fma_f32 v153, -v152, v123, v101
	v_cmp_ge_f32_e64 s[0:1], 0, v153
	v_add_u32_e32 v153, 1, v123
	s_nop 0
	v_cndmask_b32_e64 v152, v123, v152, s[0:1]
	v_fma_f32 v123, -v153, v123, v101
	v_cmp_lt_f32_e64 s[0:1], 0, v123
	s_nop 1
	v_cndmask_b32_e64 v123, v152, v153, s[0:1]
	v_mul_f32_e32 v152, 0x37800000, v123
	v_cndmask_b32_e32 v123, v123, v152, vcc
	v_cmp_class_f32_e32 vcc, v101, v189
	s_nop 1
	v_cndmask_b32_e32 v101, v123, v101, vcc
	v_div_scale_f32 v123, s[0:1], v101, v101, 1.0
	v_rcp_f32_e32 v152, v123
	s_nop 0
	v_fma_f32 v153, -v123, v152, 1.0
	v_fmac_f32_e32 v152, v153, v152
	v_div_scale_f32 v153, vcc, 1.0, v101, 1.0
	v_mul_f32_e32 v154, v153, v152
	v_fma_f32 v155, -v123, v154, v153
	v_fmac_f32_e32 v154, v155, v152
	v_fma_f32 v123, -v123, v154, v153
	v_div_fmas_f32 v123, v123, v152, v154
	v_div_fixup_f32 v101, v123, v101, 1.0
	v_mul_f32_e32 v98, v98, v101
	v_mul_f32_e32 v100, v100, v101
	v_mul_f32_e32 v0, v0, v101
	v_mul_f32_e32 v99, v99, v101
	v_fma_f32 v97, v3, v100, v97
	v_fma_f32 v95, v5, v98, v95
	v_fma_f32 v96, v2, v99, v96
	v_fmac_f32_e32 v94, v4, v0
	v_mul_f32_e32 v0, v95, v95
	v_mul_f32_e32 v100, v97, v97
	v_fmac_f32_e32 v0, v94, v94
	v_fmac_f32_e32 v100, v96, v96
	v_add_f32_e32 v0, v0, v100
	v_mul_f32_e32 v100, v102, v101
	v_mul_f32_e32 v102, v103, v101
	v_mul_f32_e32 v103, v104, v101
	v_mul_f32_e32 v104, v105, v101
	v_fma_f32 v93, v15, v104, v93
	v_fma_f32 v91, v17, v102, v91
	v_fma_f32 v92, v14, v103, v92
	v_fmac_f32_e32 v90, v16, v100
	v_mul_f32_e32 v100, v91, v91
	v_mul_f32_e32 v102, v93, v93
	v_fmac_f32_e32 v100, v90, v90
	v_fmac_f32_e32 v102, v92, v92
	v_add_f32_e32 v100, v100, v102
	v_mul_f32_e32 v102, v107, v101
	v_mul_f32_e32 v104, v109, v101
	v_add_f32_e32 v0, v0, v100
	v_mul_f32_e32 v100, v106, v101
	v_mul_f32_e32 v103, v108, v101
	v_fma_f32 v89, v27, v104, v89
	v_fma_f32 v87, v29, v102, v87
	v_fma_f32 v88, v26, v103, v88
	v_fmac_f32_e32 v86, v28, v100
	v_mul_f32_e32 v100, v87, v87
	v_mul_f32_e32 v102, v89, v89
	v_fmac_f32_e32 v100, v86, v86
	v_fmac_f32_e32 v102, v88, v88
	v_add_f32_e32 v100, v100, v102
	v_add_f32_e32 v0, v100, v0
	v_mul_f32_e32 v100, v110, v101
	v_mul_f32_e32 v102, v111, v101
	v_mul_f32_e32 v103, v112, v101
	v_mul_f32_e32 v101, v113, v101
	v_lshl_add_u64 v[98:99], v[120:121], 0, v[150:151]
	v_fma_f32 v85, v39, v101, v85
	v_fma_f32 v84, v38, v103, v84
	v_fma_f32 v83, v41, v102, v83
	v_fmac_f32_e32 v82, v40, v100
	s_nop 1
	s_nop 1
	s_nop 1
	s_nop 1
	v_mul_f32_e32 v98, v83, v83
	v_mul_f32_e32 v99, v85, v85
	v_fmac_f32_e32 v98, v82, v82
	v_fmac_f32_e32 v99, v84, v84
	v_add_f32_e32 v98, v98, v99
	v_add_f32_e32 v0, v98, v0
	s_nop 1
	v_add_f32_dpp v0, v0, v0 quad_perm:[1,0,3,2] row_mask:0xf bank_mask:0xf bound_ctrl:1
	s_nop 1
	v_add_f32_dpp v0, v0, v0 quad_perm:[2,3,0,1] row_mask:0xf bank_mask:0xf bound_ctrl:1
	s_nop 1
	v_add_f32_dpp v0, v0, v0 row_half_mirror row_mask:0xf bank_mask:0xf bound_ctrl:1
	s_nop 1
	v_add_f32_dpp v0, v0, v0 row_mirror row_mask:0xf bank_mask:0xf bound_ctrl:1
	s_nop 0
	v_readlane_b32 s1, v0, 16
	v_readlane_b32 s6, v0, 48
	v_readlane_b32 s0, v0, 0
	v_readlane_b32 s2, v0, 32
	v_mov_b32_e32 v0, s1
	v_mov_b32_e32 v98, s6
	v_add_f32_e32 v0, s0, v0
	v_add_f32_e32 v98, s2, v98
	v_add_f32_e32 v0, v0, v98
	v_fmamk_f32 v0, v0, 0x3a800000, v188
	v_cmp_gt_f32_e32 vcc, s49, v0
	v_mul_f32_e32 v98, 0x4f800000, v0
	s_nop 0
	v_cndmask_b32_e32 v0, v0, v98, vcc
	v_sqrt_f32_e32 v98, v0
	s_nop 0
	v_add_u32_e32 v99, -1, v98
	v_fma_f32 v100, -v99, v98, v0
	v_cmp_ge_f32_e64 s[0:1], 0, v100
	v_add_u32_e32 v100, 1, v98
	s_nop 0
	v_cndmask_b32_e64 v99, v98, v99, s[0:1]
	v_fma_f32 v98, -v100, v98, v0
	v_cmp_lt_f32_e64 s[0:1], 0, v98
	s_nop 1
	v_cndmask_b32_e64 v98, v99, v100, s[0:1]
	v_mul_f32_e32 v99, 0x37800000, v98
	v_cndmask_b32_e32 v98, v98, v99, vcc
	v_cmp_class_f32_e32 vcc, v0, v189
	s_nop 1
	v_cndmask_b32_e32 v0, v98, v0, vcc
	v_div_scale_f32 v98, s[0:1], v0, v0, 1.0
	v_rcp_f32_e32 v99, v98
	s_nop 0
	v_fma_f32 v100, -v98, v99, 1.0
	v_fmac_f32_e32 v99, v100, v99
	v_div_scale_f32 v100, vcc, 1.0, v0, 1.0
	v_mul_f32_e32 v101, v100, v99
	v_fma_f32 v102, -v98, v101, v100
	v_fmac_f32_e32 v101, v102, v99
	v_fma_f32 v98, -v98, v101, v100
	v_div_fmas_f32 v98, v98, v99, v101
	v_div_fixup_f32 v0, v98, v0, 1.0
	v_mul_f32_e32 v95, v95, v0
	v_mul_f32_e32 v94, v94, v0
	v_mul_f32_e32 v91, v91, v0
	v_mul_f32_e32 v90, v90, v0
	v_mul_f32_e32 v87, v87, v0
	v_mul_f32_e32 v86, v86, v0
	v_mul_f32_e32 v82, v82, v0
	v_lshl_add_u64 v[98:99], v[118:119], 0, v[140:141]
	v_mul_f32_e32 v97, v97, v0
	v_mul_f32_e32 v96, v96, v0
	v_fma_f32 v94, v8, v94, v10
	v_fma_f32 v95, v9, v95, v11
	v_mul_f32_e32 v93, v93, v0
	v_mul_f32_e32 v92, v92, v0
	v_fma_f32 v90, v20, v90, v22
	v_fma_f32 v91, v21, v91, v23
	v_mul_f32_e32 v89, v89, v0
	v_mul_f32_e32 v88, v88, v0
	v_fma_f32 v86, v32, v86, v34
	v_fma_f32 v87, v33, v87, v35
	v_mul_f32_e32 v83, v83, v0
	v_mul_f32_e32 v85, v85, v0
	v_fma_f32 v82, v44, v82, v46
	v_fma_f32 v96, v6, v96, v12
	v_fma_f32 v97, v7, v97, v13
	v_cvt_pk_bf16_f32 v94, v94, v95
	v_cvt_pk_bf16_f32 v95, v96, v97
	global_store_dwordx2 v[98:99], v[94:95], off sc1
	v_fma_f32 v92, v18, v92, v24
	v_fma_f32 v93, v19, v93, v25
	v_cvt_pk_bf16_f32 v90, v90, v91
	v_cvt_pk_bf16_f32 v91, v92, v93
	global_store_dwordx2 v[98:99], v[90:91], off offset:512 sc1
	v_fma_f32 v88, v30, v88, v36
	v_fma_f32 v89, v31, v89, v37
	v_cvt_pk_bf16_f32 v86, v86, v87
	v_cvt_pk_bf16_f32 v87, v88, v89
	global_store_dwordx2 v[98:99], v[86:87], off offset:1024 sc1
	v_mul_f32_e32 v0, v84, v0
	v_fma_f32 v84, v43, v85, v49
	v_fma_f32 v83, v45, v83, v47
	v_cvt_pk_bf16_f32 v82, v82, v83
	v_fma_f32 v0, v42, v0, v48
	v_cvt_pk_bf16_f32 v83, v0, v84
	global_store_dwordx2 v[98:99], v[82:83], off offset:1536 sc1
	s_waitcnt vmcnt(22)
	v_and_b32_e32 v82, 0xffff0000, v148
	v_and_b32_e32 v84, 0xffff0000, v149
	v_lshlrev_b32_e32 v0, 16, v148
	v_lshlrev_b32_e32 v83, 16, v149
	v_mul_f32_e32 v85, v82, v82
	v_mul_f32_e32 v86, v84, v84
	v_fmac_f32_e32 v85, v0, v0
	v_fmac_f32_e32 v86, v83, v83
	s_waitcnt vmcnt(20)
	v_and_b32_e32 v87, 0xffff0000, v146
	v_and_b32_e32 v89, 0xffff0000, v147
	v_add_f32_e32 v85, v85, v86
	v_lshlrev_b32_e32 v86, 16, v146
	v_lshlrev_b32_e32 v88, 16, v147
	v_mul_f32_e32 v90, v87, v87
	v_mul_f32_e32 v91, v89, v89
	v_fmac_f32_e32 v90, v86, v86
	v_fmac_f32_e32 v91, v88, v88
	v_add_f32_e32 v90, v90, v91
	s_waitcnt vmcnt(18)
	v_and_b32_e32 v91, 0xffff0000, v144
	v_and_b32_e32 v93, 0xffff0000, v145
	v_add_f32_e32 v85, v85, v90
	v_lshlrev_b32_e32 v90, 16, v144
	v_lshlrev_b32_e32 v92, 16, v145
	v_mul_f32_e32 v94, v91, v91
	v_mul_f32_e32 v95, v93, v93
	v_fmac_f32_e32 v94, v90, v90
	v_fmac_f32_e32 v95, v92, v92
	v_add_f32_e32 v94, v94, v95
	s_waitcnt vmcnt(16)
	v_and_b32_e32 v95, 0xffff0000, v142
	v_and_b32_e32 v97, 0xffff0000, v143
	v_add_f32_e32 v85, v85, v94
	v_lshlrev_b32_e32 v94, 16, v142
	v_lshlrev_b32_e32 v96, 16, v143
	v_mul_f32_e32 v98, v95, v95
	v_mul_f32_e32 v99, v97, v97
	v_fmac_f32_e32 v98, v94, v94
	v_fmac_f32_e32 v99, v96, v96
	v_add_f32_e32 v98, v98, v99
	v_add_f32_e32 v85, v85, v98
	s_nop 1
	v_add_f32_dpp v85, v85, v85 quad_perm:[1,0,3,2] row_mask:0xf bank_mask:0xf bound_ctrl:1
	s_nop 1
	v_add_f32_dpp v85, v85, v85 quad_perm:[2,3,0,1] row_mask:0xf bank_mask:0xf bound_ctrl:1
	s_nop 1
	v_add_f32_dpp v85, v85, v85 row_half_mirror row_mask:0xf bank_mask:0xf bound_ctrl:1
	s_nop 1
	v_add_f32_dpp v85, v85, v85 row_mirror row_mask:0xf bank_mask:0xf bound_ctrl:1
	s_nop 0
	v_readlane_b32 s1, v85, 16
	v_readlane_b32 s6, v85, 48
	v_readlane_b32 s0, v85, 0
	v_readlane_b32 s2, v85, 32
	v_mov_b32_e32 v85, s1
	v_mov_b32_e32 v98, s6
	v_add_f32_e32 v85, s0, v85
	v_add_f32_e32 v98, s2, v98
	v_add_f32_e32 v85, v85, v98
	v_fmamk_f32 v85, v85, 0x3a800000, v188
	v_cmp_gt_f32_e32 vcc, s49, v85
	v_mul_f32_e32 v98, 0x4f800000, v85
	s_nop 0
	v_cndmask_b32_e32 v85, v85, v98, vcc
	v_sqrt_f32_e32 v98, v85
	s_nop 0
	v_add_u32_e32 v99, -1, v98
	v_fma_f32 v100, -v99, v98, v85
	v_cmp_ge_f32_e64 s[0:1], 0, v100
	v_add_u32_e32 v100, 1, v98
	s_nop 0
	v_cndmask_b32_e64 v99, v98, v99, s[0:1]
	v_fma_f32 v98, -v100, v98, v85
	v_cmp_lt_f32_e64 s[0:1], 0, v98
	s_nop 1
	v_cndmask_b32_e64 v98, v99, v100, s[0:1]
	v_mul_f32_e32 v99, 0x37800000, v98
	v_cndmask_b32_e32 v98, v98, v99, vcc
	v_cmp_class_f32_e32 vcc, v85, v189
	s_nop 1
	v_cndmask_b32_e32 v85, v98, v85, vcc
	v_div_scale_f32 v98, s[0:1], v85, v85, 1.0
	v_rcp_f32_e32 v99, v98
	s_nop 0
	v_fma_f32 v100, -v98, v99, 1.0
	v_fmac_f32_e32 v99, v100, v99
	v_div_scale_f32 v100, vcc, 1.0, v85, 1.0
	v_mul_f32_e32 v101, v100, v99
	v_fma_f32 v102, -v98, v101, v100
	v_fmac_f32_e32 v101, v102, v99
	v_fma_f32 v98, -v98, v101, v100
	v_div_fmas_f32 v98, v98, v99, v101
	v_div_fixup_f32 v85, v98, v85, 1.0
	v_mul_f32_e32 v82, v82, v85
	v_mul_f32_e32 v84, v84, v85
	v_mul_f32_e32 v0, v0, v85
	v_mul_f32_e32 v83, v83, v85
	v_fma_f32 v81, v3, v84, v81
	v_fma_f32 v79, v5, v82, v79
	v_fma_f32 v80, v2, v83, v80
	v_fmac_f32_e32 v78, v4, v0
	v_mul_f32_e32 v0, v79, v79
	v_mul_f32_e32 v84, v81, v81
	v_fmac_f32_e32 v0, v78, v78
	v_fmac_f32_e32 v84, v80, v80
	v_add_f32_e32 v0, v0, v84
	v_mul_f32_e32 v84, v86, v85
	v_mul_f32_e32 v86, v87, v85
	v_mul_f32_e32 v87, v88, v85
	v_mul_f32_e32 v88, v89, v85
	v_fma_f32 v77, v15, v88, v77
	v_fma_f32 v75, v17, v86, v75
	v_fma_f32 v76, v14, v87, v76
	v_fmac_f32_e32 v74, v16, v84
	v_mul_f32_e32 v84, v75, v75
	v_mul_f32_e32 v86, v77, v77
	v_fmac_f32_e32 v84, v74, v74
	v_fmac_f32_e32 v86, v76, v76
	v_add_f32_e32 v84, v84, v86
	v_mul_f32_e32 v86, v91, v85
	v_mul_f32_e32 v88, v93, v85
	v_add_f32_e32 v0, v0, v84
	v_mul_f32_e32 v84, v90, v85
	v_mul_f32_e32 v87, v92, v85
	v_fma_f32 v73, v27, v88, v73
	v_fma_f32 v71, v29, v86, v71
	v_fma_f32 v72, v26, v87, v72
	v_fmac_f32_e32 v70, v28, v84
	v_mul_f32_e32 v84, v71, v71
	v_mul_f32_e32 v86, v73, v73
	v_fmac_f32_e32 v84, v70, v70
	v_fmac_f32_e32 v86, v72, v72
	v_add_f32_e32 v84, v84, v86
	v_add_f32_e32 v0, v84, v0
	v_mul_f32_e32 v84, v94, v85
	v_mul_f32_e32 v86, v95, v85
	v_mul_f32_e32 v87, v96, v85
	v_mul_f32_e32 v85, v97, v85
	v_lshl_add_u64 v[82:83], v[120:121], 0, v[138:139]
	v_fma_f32 v69, v39, v85, v69
	v_fma_f32 v68, v38, v87, v68
	v_fma_f32 v67, v41, v86, v67
	v_fmac_f32_e32 v66, v40, v84
	s_nop 1
	s_nop 1
	s_nop 1
	s_nop 1
	v_mul_f32_e32 v82, v67, v67
	v_mul_f32_e32 v83, v69, v69
	v_fmac_f32_e32 v82, v66, v66
	v_fmac_f32_e32 v83, v68, v68
	v_add_f32_e32 v82, v82, v83
	v_add_f32_e32 v0, v82, v0
	s_nop 1
	v_add_f32_dpp v0, v0, v0 quad_perm:[1,0,3,2] row_mask:0xf bank_mask:0xf bound_ctrl:1
	s_nop 1
	v_add_f32_dpp v0, v0, v0 quad_perm:[2,3,0,1] row_mask:0xf bank_mask:0xf bound_ctrl:1
	s_nop 1
	v_add_f32_dpp v0, v0, v0 row_half_mirror row_mask:0xf bank_mask:0xf bound_ctrl:1
	s_nop 1
	v_add_f32_dpp v0, v0, v0 row_mirror row_mask:0xf bank_mask:0xf bound_ctrl:1
	s_nop 0
	v_readlane_b32 s1, v0, 16
	v_readlane_b32 s6, v0, 48
	v_readlane_b32 s0, v0, 0
	v_readlane_b32 s2, v0, 32
	v_mov_b32_e32 v0, s1
	v_mov_b32_e32 v82, s6
	v_add_f32_e32 v0, s0, v0
	v_add_f32_e32 v82, s2, v82
	v_add_f32_e32 v0, v0, v82
	v_fmamk_f32 v0, v0, 0x3a800000, v188
	v_cmp_gt_f32_e32 vcc, s49, v0
	v_mul_f32_e32 v82, 0x4f800000, v0
	s_nop 0
	v_cndmask_b32_e32 v0, v0, v82, vcc
	v_sqrt_f32_e32 v82, v0
	s_nop 0
	v_add_u32_e32 v83, -1, v82
	v_fma_f32 v84, -v83, v82, v0
	v_cmp_ge_f32_e64 s[0:1], 0, v84
	v_add_u32_e32 v84, 1, v82
	s_nop 0
	v_cndmask_b32_e64 v83, v82, v83, s[0:1]
	v_fma_f32 v82, -v84, v82, v0
	v_cmp_lt_f32_e64 s[0:1], 0, v82
	s_nop 1
	v_cndmask_b32_e64 v82, v83, v84, s[0:1]
	v_mul_f32_e32 v83, 0x37800000, v82
	v_cndmask_b32_e32 v82, v82, v83, vcc
	v_cmp_class_f32_e32 vcc, v0, v189
	s_nop 1
	v_cndmask_b32_e32 v0, v82, v0, vcc
	v_div_scale_f32 v82, s[0:1], v0, v0, 1.0
	v_rcp_f32_e32 v83, v82
	s_nop 0
	v_fma_f32 v84, -v82, v83, 1.0
	v_fmac_f32_e32 v83, v84, v83
	v_div_scale_f32 v84, vcc, 1.0, v0, 1.0
	v_mul_f32_e32 v85, v84, v83
	v_fma_f32 v86, -v82, v85, v84
	v_fmac_f32_e32 v85, v86, v83
	v_fma_f32 v82, -v82, v85, v84
	v_div_fmas_f32 v82, v82, v83, v85
	v_div_fixup_f32 v0, v82, v0, 1.0
	v_mul_f32_e32 v79, v79, v0
	v_mul_f32_e32 v78, v78, v0
	v_mul_f32_e32 v75, v75, v0
	v_mul_f32_e32 v74, v74, v0
	v_mul_f32_e32 v71, v71, v0
	v_mul_f32_e32 v70, v70, v0
	v_mul_f32_e32 v66, v66, v0
	v_lshl_add_u64 v[82:83], v[118:119], 0, v[136:137]
	v_mul_f32_e32 v81, v81, v0
	v_mul_f32_e32 v80, v80, v0
	v_fma_f32 v78, v8, v78, v10
	v_fma_f32 v79, v9, v79, v11
	v_mul_f32_e32 v77, v77, v0
	v_mul_f32_e32 v76, v76, v0
	v_fma_f32 v74, v20, v74, v22
	v_fma_f32 v75, v21, v75, v23
	v_mul_f32_e32 v73, v73, v0
	v_mul_f32_e32 v72, v72, v0
	v_fma_f32 v70, v32, v70, v34
	v_fma_f32 v71, v33, v71, v35
	v_mul_f32_e32 v67, v67, v0
	v_mul_f32_e32 v69, v69, v0
	v_fma_f32 v66, v44, v66, v46
	v_fma_f32 v80, v6, v80, v12
	v_fma_f32 v81, v7, v81, v13
	v_cvt_pk_bf16_f32 v78, v78, v79
	v_cvt_pk_bf16_f32 v79, v80, v81
	global_store_dwordx2 v[82:83], v[78:79], off sc1
	v_fma_f32 v76, v18, v76, v24
	v_fma_f32 v77, v19, v77, v25
	v_cvt_pk_bf16_f32 v74, v74, v75
	v_cvt_pk_bf16_f32 v75, v76, v77
	global_store_dwordx2 v[82:83], v[74:75], off offset:512 sc1
	v_fma_f32 v72, v30, v72, v36
	v_fma_f32 v73, v31, v73, v37
	v_cvt_pk_bf16_f32 v70, v70, v71
	v_cvt_pk_bf16_f32 v71, v72, v73
	global_store_dwordx2 v[82:83], v[70:71], off offset:1024 sc1
	v_mul_f32_e32 v0, v68, v0
	v_fma_f32 v68, v43, v69, v49
	v_fma_f32 v67, v45, v67, v47
	v_cvt_pk_bf16_f32 v66, v66, v67
	v_fma_f32 v0, v42, v0, v48
	v_cvt_pk_bf16_f32 v67, v0, v68
	global_store_dwordx2 v[82:83], v[66:67], off offset:1536 sc1
	s_waitcnt vmcnt(18)
	v_and_b32_e32 v66, 0xffff0000, v134
	v_and_b32_e32 v68, 0xffff0000, v135
	v_lshlrev_b32_e32 v0, 16, v134
	v_lshlrev_b32_e32 v67, 16, v135
	v_mul_f32_e32 v69, v66, v66
	v_mul_f32_e32 v70, v68, v68
	v_fmac_f32_e32 v69, v0, v0
	v_fmac_f32_e32 v70, v67, v67
	v_add_f32_e32 v73, v69, v70
	s_waitcnt vmcnt(16)
	v_and_b32_e32 v70, 0xffff0000, v132
	v_and_b32_e32 v72, 0xffff0000, v133
	v_lshlrev_b32_e32 v69, 16, v132
	v_lshlrev_b32_e32 v71, 16, v133
	v_mul_f32_e32 v74, v70, v70
	v_mul_f32_e32 v75, v72, v72
	v_fmac_f32_e32 v74, v69, v69
	v_fmac_f32_e32 v75, v71, v71
	v_add_f32_e32 v74, v74, v75
	v_add_f32_e32 v77, v73, v74
	s_waitcnt vmcnt(14)
	v_and_b32_e32 v74, 0xffff0000, v130
	v_and_b32_e32 v76, 0xffff0000, v131
	v_lshlrev_b32_e32 v73, 16, v130
	v_lshlrev_b32_e32 v75, 16, v131
	v_mul_f32_e32 v78, v74, v74
	v_mul_f32_e32 v79, v76, v76
	v_fmac_f32_e32 v78, v73, v73
	v_fmac_f32_e32 v79, v75, v75
	v_add_f32_e32 v78, v78, v79
	v_add_f32_e32 v81, v77, v78
	s_waitcnt vmcnt(12)
	v_and_b32_e32 v78, 0xffff0000, v128
	v_and_b32_e32 v80, 0xffff0000, v129
	v_lshlrev_b32_e32 v77, 16, v128
	v_lshlrev_b32_e32 v79, 16, v129
	v_mul_f32_e32 v82, v78, v78
	v_mul_f32_e32 v83, v80, v80
	v_fmac_f32_e32 v82, v77, v77
	v_fmac_f32_e32 v83, v79, v79
	v_add_f32_e32 v82, v82, v83
	v_add_f32_e32 v81, v81, v82
	s_nop 1
	v_add_f32_dpp v81, v81, v81 quad_perm:[1,0,3,2] row_mask:0xf bank_mask:0xf bound_ctrl:1
	s_nop 1
	v_add_f32_dpp v81, v81, v81 quad_perm:[2,3,0,1] row_mask:0xf bank_mask:0xf bound_ctrl:1
	s_nop 1
	v_add_f32_dpp v81, v81, v81 row_half_mirror row_mask:0xf bank_mask:0xf bound_ctrl:1
	s_nop 1
	v_add_f32_dpp v81, v81, v81 row_mirror row_mask:0xf bank_mask:0xf bound_ctrl:1
	s_nop 0
	v_readlane_b32 s6, v81, 16
	v_readlane_b32 s1, v81, 48
	v_readlane_b32 s2, v81, 0
	v_readlane_b32 s0, v81, 32
	v_mov_b32_e32 v81, s6
	v_mov_b32_e32 v82, s1
	v_add_f32_e32 v81, s2, v81
	v_add_f32_e32 v82, s0, v82
	v_add_f32_e32 v81, v81, v82
	v_fmamk_f32 v81, v81, 0x3a800000, v188
	v_cmp_gt_f32_e32 vcc, s49, v81
	v_mul_f32_e32 v82, 0x4f800000, v81
	s_nop 0
	v_cndmask_b32_e32 v81, v81, v82, vcc
	v_sqrt_f32_e32 v82, v81
	s_nop 0
	v_add_u32_e32 v83, -1, v82
	v_fma_f32 v84, -v83, v82, v81
	v_cmp_ge_f32_e64 s[0:1], 0, v84
	v_add_u32_e32 v84, 1, v82
	s_nop 0
	v_cndmask_b32_e64 v83, v82, v83, s[0:1]
	v_fma_f32 v82, -v84, v82, v81
	v_cmp_lt_f32_e64 s[0:1], 0, v82
	s_nop 1
	v_cndmask_b32_e64 v82, v83, v84, s[0:1]
	v_mul_f32_e32 v83, 0x37800000, v82
	v_cndmask_b32_e32 v82, v82, v83, vcc
	v_cmp_class_f32_e32 vcc, v81, v189
	s_nop 1
	v_cndmask_b32_e32 v81, v82, v81, vcc
	v_div_scale_f32 v82, s[0:1], v81, v81, 1.0
	v_rcp_f32_e32 v83, v82
	s_nop 0
	v_fma_f32 v84, -v82, v83, 1.0
	v_fmac_f32_e32 v83, v84, v83
	v_div_scale_f32 v84, vcc, 1.0, v81, 1.0
	v_mul_f32_e32 v85, v84, v83
	v_fma_f32 v86, -v82, v85, v84
	v_fmac_f32_e32 v85, v86, v83
	v_fma_f32 v82, -v82, v85, v84
	v_div_fmas_f32 v82, v82, v83, v85
	v_div_fixup_f32 v81, v82, v81, 1.0
	v_mul_f32_e32 v66, v66, v81
	v_mul_f32_e32 v68, v68, v81
	v_mul_f32_e32 v0, v0, v81
	v_mul_f32_e32 v67, v67, v81
	v_fma_f32 v65, v3, v68, v65
	v_fma_f32 v63, v5, v66, v63
	v_fma_f32 v64, v2, v67, v64
	v_fmac_f32_e32 v62, v4, v0
	v_mul_f32_e32 v0, v63, v63
	v_mul_f32_e32 v68, v65, v65
	v_fmac_f32_e32 v0, v62, v62
	v_fmac_f32_e32 v68, v64, v64
	v_add_f32_e32 v0, v0, v68
	v_mul_f32_e32 v68, v69, v81
	v_mul_f32_e32 v69, v70, v81
	v_mul_f32_e32 v70, v71, v81
	v_mul_f32_e32 v71, v72, v81
	v_fma_f32 v61, v15, v71, v61
	v_fma_f32 v59, v17, v69, v59
	v_fma_f32 v60, v14, v70, v60
	v_fmac_f32_e32 v58, v16, v68
	v_mul_f32_e32 v68, v59, v59
	v_mul_f32_e32 v69, v61, v61
	v_fmac_f32_e32 v68, v58, v58
	v_fmac_f32_e32 v69, v60, v60
	v_add_f32_e32 v68, v68, v69
	v_mul_f32_e32 v69, v74, v81
	v_mul_f32_e32 v71, v76, v81
	v_add_f32_e32 v0, v0, v68
	v_mul_f32_e32 v68, v73, v81
	v_mul_f32_e32 v70, v75, v81
	v_fma_f32 v57, v27, v71, v57
	v_fma_f32 v55, v29, v69, v55
	v_fma_f32 v56, v26, v70, v56
	v_fmac_f32_e32 v54, v28, v68
	v_mul_f32_e32 v68, v55, v55
	v_mul_f32_e32 v69, v57, v57
	v_fmac_f32_e32 v68, v54, v54
	v_fmac_f32_e32 v69, v56, v56
	v_add_f32_e32 v68, v68, v69
	v_add_f32_e32 v0, v68, v0
	v_mul_f32_e32 v68, v77, v81
	v_mul_f32_e32 v69, v78, v81
	v_mul_f32_e32 v70, v79, v81
	v_mul_f32_e32 v71, v80, v81
	v_lshl_add_u64 v[66:67], v[120:121], 0, v[126:127]
	v_fma_f32 v53, v39, v71, v53
	v_fma_f32 v52, v38, v70, v52
	v_fma_f32 v51, v41, v69, v51
	v_fmac_f32_e32 v50, v40, v68
	s_nop 1
	s_nop 1
	s_nop 1
	s_nop 1
	v_mul_f32_e32 v66, v51, v51
	v_mul_f32_e32 v67, v53, v53
	v_fmac_f32_e32 v66, v50, v50
	v_fmac_f32_e32 v67, v52, v52
	v_add_f32_e32 v66, v66, v67
	v_add_f32_e32 v0, v66, v0
	s_nop 1
	v_add_f32_dpp v0, v0, v0 quad_perm:[1,0,3,2] row_mask:0xf bank_mask:0xf bound_ctrl:1
	s_nop 1
	v_add_f32_dpp v0, v0, v0 quad_perm:[2,3,0,1] row_mask:0xf bank_mask:0xf bound_ctrl:1
	s_nop 1
	v_add_f32_dpp v0, v0, v0 row_half_mirror row_mask:0xf bank_mask:0xf bound_ctrl:1
	s_nop 1
	v_add_f32_dpp v0, v0, v0 row_mirror row_mask:0xf bank_mask:0xf bound_ctrl:1
	s_nop 0
	v_readlane_b32 s1, v0, 16
	v_readlane_b32 s6, v0, 48
	v_readlane_b32 s0, v0, 0
	v_readlane_b32 s2, v0, 32
	v_mov_b32_e32 v0, s1
	v_mov_b32_e32 v66, s6
	v_add_f32_e32 v0, s0, v0
	v_add_f32_e32 v66, s2, v66
	v_add_f32_e32 v0, v0, v66
	v_fmamk_f32 v0, v0, 0x3a800000, v188
	v_cmp_gt_f32_e32 vcc, s49, v0
	v_mul_f32_e32 v66, 0x4f800000, v0
	s_nop 0
	v_cndmask_b32_e32 v0, v0, v66, vcc
	v_sqrt_f32_e32 v66, v0
	s_nop 0
	v_add_u32_e32 v67, -1, v66
	v_fma_f32 v68, -v67, v66, v0
	v_cmp_ge_f32_e64 s[0:1], 0, v68
	v_add_u32_e32 v68, 1, v66
	s_nop 0
	v_cndmask_b32_e64 v67, v66, v67, s[0:1]
	v_fma_f32 v66, -v68, v66, v0
	v_cmp_lt_f32_e64 s[0:1], 0, v66
	s_nop 1
	v_cndmask_b32_e64 v66, v67, v68, s[0:1]
	v_mul_f32_e32 v67, 0x37800000, v66
	v_cndmask_b32_e32 v66, v66, v67, vcc
	v_cmp_class_f32_e32 vcc, v0, v189
	s_nop 1
	v_cndmask_b32_e32 v0, v66, v0, vcc
	v_div_scale_f32 v66, s[0:1], v0, v0, 1.0
	v_rcp_f32_e32 v67, v66
	s_nop 0
	v_fma_f32 v68, -v66, v67, 1.0
	v_fmac_f32_e32 v67, v68, v67
	v_div_scale_f32 v68, vcc, 1.0, v0, 1.0
	v_mul_f32_e32 v69, v68, v67
	v_fma_f32 v70, -v66, v69, v68
	v_fmac_f32_e32 v69, v70, v67
	v_fma_f32 v66, -v66, v69, v68
	v_div_fmas_f32 v66, v66, v67, v69
	v_div_fixup_f32 v0, v66, v0, 1.0
	v_mul_f32_e32 v63, v63, v0
	v_mul_f32_e32 v62, v62, v0
	v_mul_f32_e32 v59, v59, v0
	v_mul_f32_e32 v58, v58, v0
	v_mul_f32_e32 v55, v55, v0
	v_mul_f32_e32 v54, v54, v0
	v_mul_f32_e32 v51, v51, v0
	v_mul_f32_e32 v50, v50, v0
	v_cmp_lt_i32_e32 vcc, s61, v172
	v_lshl_add_u64 v[66:67], v[118:119], 0, v[124:125]
	v_mul_f32_e32 v65, v65, v0
	v_mul_f32_e32 v64, v64, v0
	v_fma_f32 v62, v8, v62, v10
	v_fma_f32 v63, v9, v63, v11
	v_mul_f32_e32 v61, v61, v0
	v_mul_f32_e32 v60, v60, v0
	v_fma_f32 v58, v20, v58, v22
	v_fma_f32 v59, v21, v59, v23
	v_mul_f32_e32 v57, v57, v0
	v_mul_f32_e32 v56, v56, v0
	v_fma_f32 v54, v32, v54, v34
	v_fma_f32 v55, v33, v55, v35
	v_mul_f32_e32 v53, v53, v0
	v_mul_f32_e32 v0, v52, v0
	v_fma_f32 v50, v44, v50, v46
	v_fma_f32 v51, v45, v51, v47
	s_or_b64 s[42:43], vcc, s[42:43]
	v_fma_f32 v64, v6, v64, v12
	v_fma_f32 v65, v7, v65, v13
	v_cvt_pk_bf16_f32 v62, v62, v63
	v_cvt_pk_bf16_f32 v63, v64, v65
	global_store_dwordx2 v[66:67], v[62:63], off sc1
	v_fma_f32 v60, v18, v60, v24
	v_fma_f32 v61, v19, v61, v25
	v_cvt_pk_bf16_f32 v58, v58, v59
	v_cvt_pk_bf16_f32 v59, v60, v61
	global_store_dwordx2 v[66:67], v[58:59], off offset:512 sc1
	v_fma_f32 v56, v30, v56, v36
	v_fma_f32 v57, v31, v57, v37
	v_cvt_pk_bf16_f32 v54, v54, v55
	v_cvt_pk_bf16_f32 v55, v56, v57
	global_store_dwordx2 v[66:67], v[54:55], off offset:1024 sc1
	v_fma_f32 v0, v42, v0, v48
	v_fma_f32 v52, v43, v53, v49
	v_cvt_pk_bf16_f32 v50, v50, v51
	v_cvt_pk_bf16_f32 v51, v0, v52
	global_store_dwordx2 v[66:67], v[50:51], off offset:1536 sc1
	s_andn2_b64 exec, exec, s[42:43]
	s_cbranch_execnz .LBB0_33
